# sparse attention phase: one static s_setprio 1 for waves 4-7 (the younger half sharing SIMDs with waves 0-3), reset at the end of the phase
# baseline (speedup 1.0000x reference)
.LBB0_2063:
	s_or_b64 exec, exec, s[0:1]
	s_cmpk_gt_i32 s90, 0x3ff
	v_readlane_b32 s68, v251, 50
	v_readlane_b32 s69, v251, 51
	s_waitcnt lgkmcnt(0)
	s_barrier
	s_cbranch_scc1 .LBB0_2167
	v_readlane_b32 s0, v251, 7
	v_and_b32_e32 v112, 15, v152
	v_lshrrev_b32_e32 v113, 4, v152
	s_nop 1
	s_and_b32 s34, s0, 3
	s_lshr_b32 s35, s0, 2
	v_lshrrev_b32_e32 v220, 3, v153
	v_and_b32_e32 v221, 7, v153
	v_and_b32_e32 v222, 7, v220
	v_xor_b32_e32 v222, v222, v221
	v_lshlrev_b32_e32 v222, 4, v222
	v_lshl_add_u32 v114, v220, 7, v222
	v_mul_u32_u24_e32 v123, 0x90, v220
	v_lshl_add_u32 v123, v221, 4, v123
	v_add_u32_e32 v123, 0x2400, v123
	v_mul_u32_u24_e32 v117, 0x600, v220
	v_lshl_add_u32 v117, v221, 4, v117
	v_lshlrev_b32_e32 v118, 12, v220
	v_lshl_add_u32 v118, v221, 4, v118
	v_mul_u32_u24_e32 v116, 0x90, v112
	v_lshl_add_u32 v116, v113, 3, v116
	v_and_b32_e32 v222, 7, v112
	v_xor_b32_e32 v222, v222, v113
	v_lshlrev_b32_e32 v222, 4, v222
	v_lshl_add_u32 v115, v112, 7, v222
	v_xor_b32_e32 v122, 64, v115
	s_lshl_b32 s1, s0, 13
	s_add_i32 s1, s1, 0x9000
	v_lshl_add_u32 v250, v152, 4, s1
	v_mov_b32_e32 v226, 0xf149f2ca
	v_mov_b32_e32 v227, 0xff61b1e6
	v_mov_b32_e32 v203, 0x41000000
	v_mov_b32_e32 v238, 0
	v_mov_b32_e32 v224, 0xff800000
	s_cmp_ge_u32 s0, 4
	s_cbranch_scc0 .Lnsa_prio
	s_setprio 1
.Lnsa_prio:
	s_mov_b32 s26, s90
	s_mov_b32 s50, 0

.Lnsa_done:
	s_waitcnt vmcnt(0)
	s_setprio 0
